# IN GEMM K-loop: per-segment s_setprio flips removed, one static s_setprio 1 for waves 0-3 before the loop
# speedup vs baseline: 1.0496x; 1.0042x over previous
.LBB0_919:
	s_ashr_i32 s61, s60, 31
	s_lshl_b64 s[64:65], s[60:61], 19
	s_add_u32 s64, s28, s64
	s_addc_u32 s65, s29, s65
	s_and_b64 s[66:67], s[38:39], exec
	s_cselect_b32 s14, s65, s71
	s_cselect_b32 s24, s64, s70
	s_ashr_i32 s59, s58, 31
	s_lshl_b64 s[66:67], s[58:59], 19
	s_add_u32 s66, s1, s66
	s_addc_u32 s67, s4, s67
	s_and_b64 s[74:75], s[38:39], exec
	s_cselect_b32 s59, s67, s73
	s_cselect_b32 s61, s66, s72
	s_add_u32 s70, s70, 0x40080
	s_addc_u32 s71, s71, 0
	s_add_u32 s63, s72, 0x100
	v_mov_b32_e32 v4, 0
	s_addc_u32 vcc_lo, s73, 0
	s_mov_b32 vcc_hi, -2
	v_mov_b32_e32 v5, v4
	v_mov_b32_e32 v6, v4
	v_mov_b32_e32 v7, v4
	v_mov_b32_e32 v8, v4
	v_mov_b32_e32 v9, v4
	v_mov_b32_e32 v10, v4
	v_mov_b32_e32 v11, v4
	v_mov_b32_e32 v20, v4
	v_mov_b32_e32 v21, v4
	v_mov_b32_e32 v22, v4
	v_mov_b32_e32 v23, v4
	v_mov_b32_e32 v24, v4
	v_mov_b32_e32 v25, v4
	v_mov_b32_e32 v26, v4
	v_mov_b32_e32 v27, v4
	v_mov_b32_e32 v36, v4
	v_mov_b32_e32 v37, v4
	v_mov_b32_e32 v38, v4
	v_mov_b32_e32 v39, v4
	v_mov_b32_e32 v40, v4
	v_mov_b32_e32 v41, v4
	v_mov_b32_e32 v42, v4
	v_mov_b32_e32 v43, v4
	v_mov_b32_e32 v52, v4
	v_mov_b32_e32 v53, v4
	v_mov_b32_e32 v54, v4
	v_mov_b32_e32 v55, v4
	v_mov_b32_e32 v56, v4
	v_mov_b32_e32 v57, v4
	v_mov_b32_e32 v58, v4
	v_mov_b32_e32 v59, v4
	v_mov_b32_e32 v12, v4
	v_mov_b32_e32 v13, v4
	v_mov_b32_e32 v14, v4
	v_mov_b32_e32 v15, v4
	v_mov_b32_e32 v16, v4
	v_mov_b32_e32 v17, v4
	v_mov_b32_e32 v18, v4
	v_mov_b32_e32 v19, v4
	v_mov_b32_e32 v28, v4
	v_mov_b32_e32 v29, v4
	v_mov_b32_e32 v30, v4
	v_mov_b32_e32 v31, v4
	v_mov_b32_e32 v32, v4
	v_mov_b32_e32 v33, v4
	v_mov_b32_e32 v34, v4
	v_mov_b32_e32 v35, v4
	v_mov_b32_e32 v44, v4
	v_mov_b32_e32 v45, v4
	v_mov_b32_e32 v46, v4
	v_mov_b32_e32 v47, v4
	v_mov_b32_e32 v48, v4
	v_mov_b32_e32 v49, v4
	v_mov_b32_e32 v50, v4
	v_mov_b32_e32 v51, v4
	v_mov_b32_e32 v60, v4
	v_mov_b32_e32 v61, v4
	v_mov_b32_e32 v62, v4
	v_mov_b32_e32 v63, v4
	v_mov_b32_e32 v64, v4
	v_mov_b32_e32 v65, v4
	v_mov_b32_e32 v66, v4
	v_mov_b32_e32 v67, v4
	v_mov_b32_e32 v68, v4
	v_mov_b32_e32 v69, v4
	v_mov_b32_e32 v70, v4
	v_mov_b32_e32 v71, v4
	v_mov_b32_e32 v72, v4
	v_mov_b32_e32 v73, v4
	v_mov_b32_e32 v74, v4
	v_mov_b32_e32 v75, v4
	v_mov_b32_e32 v84, v4
	v_mov_b32_e32 v85, v4
	v_mov_b32_e32 v86, v4
	v_mov_b32_e32 v87, v4
	v_mov_b32_e32 v88, v4
	v_mov_b32_e32 v89, v4
	v_mov_b32_e32 v90, v4
	v_mov_b32_e32 v91, v4
	v_mov_b32_e32 v100, v4
	v_mov_b32_e32 v101, v4
	v_mov_b32_e32 v102, v4
	v_mov_b32_e32 v103, v4
	v_mov_b32_e32 v104, v4
	v_mov_b32_e32 v105, v4
	v_mov_b32_e32 v106, v4
	v_mov_b32_e32 v107, v4
	v_mov_b32_e32 v116, v4
	v_mov_b32_e32 v117, v4
	v_mov_b32_e32 v118, v4
	v_mov_b32_e32 v119, v4
	v_mov_b32_e32 v120, v4
	v_mov_b32_e32 v121, v4
	v_mov_b32_e32 v122, v4
	v_mov_b32_e32 v123, v4
	v_mov_b32_e32 v76, v4
	v_mov_b32_e32 v77, v4
	v_mov_b32_e32 v78, v4
	v_mov_b32_e32 v79, v4
	v_mov_b32_e32 v80, v4
	v_mov_b32_e32 v81, v4
	v_mov_b32_e32 v82, v4
	v_mov_b32_e32 v83, v4
	v_mov_b32_e32 v92, v4
	v_mov_b32_e32 v93, v4
	v_mov_b32_e32 v94, v4
	v_mov_b32_e32 v95, v4
	v_mov_b32_e32 v96, v4
	v_mov_b32_e32 v97, v4
	v_mov_b32_e32 v98, v4
	v_mov_b32_e32 v99, v4
	v_mov_b32_e32 v108, v4
	v_mov_b32_e32 v109, v4
	v_mov_b32_e32 v110, v4
	v_mov_b32_e32 v111, v4
	v_mov_b32_e32 v112, v4
	v_mov_b32_e32 v113, v4
	v_mov_b32_e32 v114, v4
	v_mov_b32_e32 v115, v4
	v_mov_b32_e32 v124, v4
	v_mov_b32_e32 v125, v4
	v_mov_b32_e32 v126, v4
	v_mov_b32_e32 v127, v4
	v_mov_b32_e32 v128, v4
	v_mov_b32_e32 v129, v4
	v_mov_b32_e32 v130, v4
	v_mov_b32_e32 v131, v4
	s_cmp_ge_u32 s80, 0x1000
	s_cbranch_scc1 .Lmy_prio_in
	s_setprio 1
